# NSA-window half loop: duplicate O copy blocks removed; cross-half sum via lo+hi dup at 7 sites
# speedup vs baseline: 1.0057x; 1.0035x over previous
; DI void prep_compress_item(const Params& P, int l, int it, LAS unsigned char* lds, int wave, int lane) {
;     ...
;         if (kv == 0) {
;             const float* g = P.in[10] + (size_t)(l * 3 + 0) * 64;
;             float ss = 0.f;
; #pragma unroll
;             for (int i = 0; i < 16; ++i) ss += acc[0][i] * acc[0][i] + acc[1][i] * acc[1][i];
;             ss += shx32(ss, lane);
;             const float rstd = 1.0f / sqrtf(ss * (1.0f / 64.0f) + RMS_EPS);
; #pragma unroll
;             for (int et = 0; et < 2; ++et)
; #pragma unroll
;                 for (int i = 0; i < 16; ++i) { const int e = 32 * et + (i & 3) + 8 * (i >> 2) + 4 * h; acc[et][i] = acc[et][i] * rstd * g[e]; }
;             const float pos = (float)(16 * n + 31);
; #pragma unroll
;             for (int i = 0; i < 4; ++i) { const int e = 4 * h + i; float c, s; rope_cs(pos, exp2f(-(float)e * 0.125f * LOG2_THETA), c, s);
;                 const float a = acc[0][i], bq = acc[0][i + 4]; acc[0][i] = a * c - bq * s; acc[0][i + 4] = bq * c + a * s; }
.LBB0_327:
	v_pk_mul_f32 v[0:1], v[26:27], v[26:27]
	v_pk_mul_f32 v[2:3], v[52:53], v[52:53]
	v_pk_fma_f32 v[0:1], v[50:51], v[50:51], v[0:1]
	v_pk_fma_f32 v[2:3], v[16:17], v[16:17], v[2:3]
	v_add_f32_e32 v0, v0, v1
	v_pk_mul_f32 v[4:5], v[54:55], v[54:55]
	v_add_f32_e32 v0, v0, v2
	v_pk_fma_f32 v[4:5], v[20:21], v[20:21], v[4:5]
	v_add_f32_e32 v0, v0, v3
	v_pk_mul_f32 v[6:7], v[56:57], v[56:57]
	v_add_f32_e32 v0, v0, v4
	v_pk_fma_f32 v[6:7], v[18:19], v[18:19], v[6:7]
	v_add_f32_e32 v0, v0, v5
	v_pk_mul_f32 v[58:59], v[8:9], v[8:9]
	v_add_f32_e32 v0, v0, v6
	v_pk_fma_f32 v[58:59], v[24:25], v[24:25], v[58:59]
	v_add_f32_e32 v0, v0, v7
	v_pk_mul_f32 v[60:61], v[10:11], v[10:11]
	v_add_f32_e32 v0, v0, v58
	v_pk_fma_f32 v[60:61], v[22:23], v[22:23], v[60:61]
	v_add_f32_e32 v0, v0, v59
	v_pk_mul_f32 v[62:63], v[12:13], v[12:13]
	v_add_f32_e32 v0, v0, v60
	v_pk_fma_f32 v[62:63], v[28:29], v[28:29], v[62:63]
	v_add_f32_e32 v0, v0, v61
	v_pk_mul_f32 v[64:65], v[14:15], v[14:15]
	v_add_f32_e32 v0, v0, v62
	v_pk_fma_f32 v[64:65], v[30:31], v[30:31], v[64:65]
	v_add_f32_e32 v0, v0, v63
	v_add_f32_e32 v0, v0, v64
	v_add_f32_e32 v0, v0, v65
	v_mov_b32_e32 v1, v0
	v_mov_b32_e32 v2, v0
	s_nop 1
	v_permlane32_swap_b32_e32 v1, v2
	v_add_f32_e32 v0, v1, v2
	v_fmamk_f32 v0, v0, 0x3c800000, v185
	v_cmp_gt_f32_e32 vcc, s83, v0
	v_mul_f32_e32 v1, 0x4f800000, v0
	s_nop 0
	v_cndmask_b32_e32 v0, v0, v1, vcc
	v_sqrt_f32_e32 v1, v0
	s_nop 0
	v_add_u32_e32 v2, -1, v1
	v_fma_f32 v3, -v2, v1, v0
	v_cmp_ge_f32_e64 s[0:1], 0, v3
	v_add_u32_e32 v3, 1, v1
	s_nop 0
	v_cndmask_b32_e64 v2, v1, v2, s[0:1]
	v_fma_f32 v1, -v3, v1, v0
	v_cmp_lt_f32_e64 s[0:1], 0, v1
	s_nop 1
	v_cndmask_b32_e64 v1, v2, v3, s[0:1]
	v_mul_f32_e32 v2, 0x37800000, v1
	v_cndmask_b32_e32 v1, v1, v2, vcc
	v_cmp_class_f32_e32 vcc, v0, v194
	s_nop 1
	v_cndmask_b32_e32 v0, v1, v0, vcc
	v_div_scale_f32 v1, s[0:1], v0, v0, 1.0
	v_rcp_f32_e32 v2, v1
	s_mov_b64 s[0:1], 0x40000
	v_fma_f32 v3, -v1, v2, 1.0
	v_fmac_f32_e32 v2, v3, v2
	v_div_scale_f32 v3, vcc, 1.0, v0, 1.0
	v_mul_f32_e32 v4, v3, v2
	v_fma_f32 v5, -v1, v4, v3
	v_fmac_f32_e32 v4, v5, v2
	v_fma_f32 v1, -v1, v4, v3
	v_div_fmas_f32 v1, v1, v2, v4
	global_load_dwordx4 v[2:5], v[36:37], off offset:64
	v_div_fixup_f32 v58, v1, v0, 1.0
	v_pk_mul_f32 v[0:1], v[24:25], v[58:59] op_sel_hi:[1,0]
	v_pk_mul_f32 v[26:27], v[26:27], v[58:59] op_sel_hi:[1,0]
	v_pk_mul_f32 v[52:53], v[52:53], v[58:59] op_sel_hi:[1,0]
	v_pk_mul_f32 v[8:9], v[8:9], v[58:59] op_sel_hi:[1,0]
	v_pk_mul_f32 v[10:11], v[10:11], v[58:59] op_sel_hi:[1,0]
	v_pk_mul_f32 v[54:55], v[54:55], v[58:59] op_sel_hi:[1,0]
	v_pk_mul_f32 v[56:57], v[56:57], v[58:59] op_sel_hi:[1,0]
	v_pk_mul_f32 v[20:21], v[20:21], v[58:59] op_sel_hi:[1,0]
	v_pk_mul_f32 v[16:17], v[16:17], v[58:59] op_sel_hi:[1,0]
	v_pk_mul_f32 v[12:13], v[12:13], v[58:59] op_sel_hi:[1,0]
	v_pk_mul_f32 v[14:15], v[14:15], v[58:59] op_sel_hi:[1,0]
	s_waitcnt vmcnt(0)
	v_pk_mul_f32 v[24:25], v[2:3], v[0:1]
	v_pk_mul_f32 v[0:1], v[22:23], v[58:59] op_sel_hi:[1,0]
	s_nop 0
	v_pk_mul_f32 v[22:23], v[0:1], v[4:5]
	global_load_dwordx4 v[0:3], v[36:37], off offset:96
	v_pk_mul_f32 v[4:5], v[28:29], v[58:59] op_sel_hi:[1,0]
	s_waitcnt vmcnt(0)
	v_pk_mul_f32 v[28:29], v[4:5], v[0:1]
	v_pk_mul_f32 v[0:1], v[30:31], v[58:59] op_sel_hi:[1,0]
	s_nop 0
	v_pk_mul_f32 v[30:31], v[0:1], v[2:3]
	global_load_dwordx4 v[0:3], v[36:37], off offset:128
	global_load_dwordx4 v[4:7], v[36:37], off offset:160
	global_load_dwordx4 v[60:63], v[36:37], off offset:192
	global_load_dwordx4 v[64:67], v[36:37], off offset:224
	s_waitcnt vmcnt(3)
	v_pk_mul_f32 v[26:27], v[26:27], v[0:1]
	v_add_u32_e32 v0, 31, v94
	v_cvt_f32_u32_e32 v39, v0
	v_pk_mul_f32 v[52:53], v[52:53], v[2:3]
	s_waitcnt vmcnt(1)
	v_pk_mul_f32 v[10:11], v[10:11], v[62:63]
	v_pk_mul_f32 v[8:9], v[8:9], v[60:61]
	v_mul_f32_e32 v0, v90, v39
	v_cvt_f64_f32_e32 v[0:1], v0
	v_mul_f64 v[2:3], v[0:1], s[4:5]
	v_rndne_f64_e32 v[2:3], v[2:3]
	v_fma_f64 v[0:1], v[0:1], s[4:5], -v[2:3]
	v_cvt_f32_f64_e32 v0, v[0:1]
	v_sin_f32_e32 v60, v0
	v_cos_f32_e32 v62, v0
	v_mul_f32_e32 v0, v91, v39
	v_cvt_f64_f32_e32 v[0:1], v0
	v_mul_f64 v[2:3], v[0:1], s[4:5]
	v_rndne_f64_e32 v[2:3], v[2:3]
	v_fma_f64 v[0:1], v[0:1], s[4:5], -v[2:3]
	v_cvt_f32_f64_e32 v0, v[0:1]
	v_sin_f32_e32 v61, v0
	v_cos_f32_e32 v63, v0
	global_load_dwordx4 v[0:3], v[36:37], off
	v_pk_mul_f32 v[54:55], v[54:55], v[4:5]
	v_pk_mul_f32 v[4:5], v[50:51], v[58:59] op_sel_hi:[1,0]
	v_pk_mul_f32 v[56:57], v[56:57], v[6:7]
	s_waitcnt vmcnt(1)
	v_pk_mul_f32 v[14:15], v[14:15], v[66:67]
	v_pk_mul_f32 v[12:13], v[12:13], v[64:65]
	s_waitcnt vmcnt(0)
	v_pk_mul_f32 v[0:1], v[0:1], v[4:5]
	global_load_dwordx4 v[4:7], v[36:37], off offset:32
	v_pk_mul_f32 v[2:3], v[2:3], v[16:17]
	v_pk_mul_f32 v[16:17], v[18:19], v[58:59] op_sel_hi:[1,0]
	s_waitcnt vmcnt(0)
	v_pk_mul_f32 v[4:5], v[4:5], v[20:21]
	s_nop 0
	v_pk_mul_f32 v[20:21], v[60:61], v[4:5]
	v_pk_mul_f32 v[6:7], v[6:7], v[16:17]
	v_pk_fma_f32 v[50:51], v[62:63], v[0:1], v[20:21] neg_lo:[0,0,1] neg_hi:[0,0,1]
	v_pk_mul_f32 v[0:1], v[60:61], v[0:1]
	s_nop 0
	v_pk_fma_f32 v[20:21], v[62:63], v[4:5], v[0:1]
	v_mul_f32_e32 v0, v92, v39
	v_cvt_f64_f32_e32 v[0:1], v0
	v_mul_f64 v[4:5], v[0:1], s[4:5]
	v_rndne_f64_e32 v[4:5], v[4:5]
	v_fma_f64 v[0:1], v[0:1], s[4:5], -v[4:5]
	v_cvt_f32_f64_e32 v1, v[0:1]
	v_sin_f32_e32 v0, v1
	v_cos_f32_e32 v4, v1
	v_mul_f32_e32 v1, v93, v39
	v_cvt_f64_f32_e32 v[60:61], v1
	v_mul_f64 v[62:63], v[60:61], s[4:5]
	v_rndne_f64_e32 v[62:63], v[62:63]
	v_fma_f64 v[60:61], v[60:61], s[4:5], -v[62:63]
	v_cvt_f32_f64_e32 v5, v[60:61]
	v_sin_f32_e32 v1, v5
	v_cos_f32_e32 v5, v5
	v_pk_mul_f32 v[16:17], v[0:1], v[6:7]
	v_pk_mul_f32 v[0:1], v[0:1], v[2:3]
	v_pk_fma_f32 v[16:17], v[4:5], v[2:3], v[16:17] neg_lo:[0,0,1] neg_hi:[0,0,1]
	v_pk_fma_f32 v[18:19], v[4:5], v[6:7], v[0:1]

; DI float ex2(float x) { return __builtin_amdgcn_exp2f(x); }
; DI void nsa_unit(const Params& P, int l, LAS char* lds, int b, int qt, int tid, int wave, int lane) {
;     ...
;     for (int st = 0; st < nst; ++st) {
;         const f32x16 s = qk_rows<0, 4>(kcL, 32 * st, qf, r, h);
;         float t[16], mx = -1e30f;
; #pragma unroll
;         for (int i = 0; i < 16; ++i) { const int n = 32 * st + (i & 3) + 8 * (i >> 2) + 4 * h; const bool ok = (16 * n + 31 <= qpos); t[i] = ok ? s[i] * c : -1e30f; mx = fmaxf(mx, t[i]); }
;         mx = fmaxf(mx, shx32(mx, lane));
;         const float mn = fmaxf(m, mx), alpha = ex2(m - mn);
;         float rs = 0.f;
; #pragma unroll
;         for (int i = 0; i < 16; ++i) rs += (t[i] > -1e29f) ? ex2(t[i] - mn) : 0.f;
;         rs += shx32(rs, lane);
;         lsum = lsum * alpha + rs; m = mn;
;     }
;     const float linv = lsum > 0.f ? 1.0f / lsum : 0.f;
;     float prevpc3 = 0.f;
.LBB0_513:
	v_mov_b32_e32 v30, v0
	ds_read_b128 v[0:3], v16
	ds_read_b128 v[18:21], v16 offset:32
	ds_read_b128 v[22:25], v16 offset:64
	ds_read_b128 v[26:29], v16 offset:96
	s_setprio 1
	s_waitcnt lgkmcnt(3)
	v_mfma_f32_32x32x16_bf16 v[0:15], v[0:3], v[96:99], 0
	s_waitcnt lgkmcnt(2)
	v_mfma_f32_32x32x16_bf16 v[0:15], v[18:21], v[100:103], v[0:15]
	s_waitcnt lgkmcnt(1)
	v_mfma_f32_32x32x16_bf16 v[0:15], v[22:25], v[104:107], v[0:15]
	s_waitcnt lgkmcnt(0)
	v_mfma_f32_32x32x16_bf16 v[0:15], v[26:29], v[108:111], v[0:15]
	s_setprio 0
	v_add_u32_e32 v18, 0xfffffe50, v17
	v_cmp_le_i32_e32 vcc, v18, v160
	v_add_u32_e32 v18, 0xfffffe60, v17
	v_add_u32_e32 v19, 0xfffffe70, v17
	s_nop 6
	v_cndmask_b32_e32 v0, v208, v0, vcc
	v_cmp_le_i32_e32 vcc, v18, v160
	s_add_i32 s1, s1, -1
	v_add_u32_e32 v16, 0x1200, v16
	v_cndmask_b32_e32 v1, v208, v1, vcc
	v_cmp_le_i32_e32 vcc, v19, v160
	v_add_u32_e32 v19, 0xfffffe80, v17
	v_max3_f32 v18, v0, s15, v1
	v_cndmask_b32_e32 v2, v208, v2, vcc
	v_cmp_le_i32_e32 vcc, v19, v160
	v_add_u32_e32 v19, 0xfffffed0, v17
	s_cmp_eq_u32 s1, 0
	v_cndmask_b32_e32 v3, v208, v3, vcc
	v_cmp_le_i32_e32 vcc, v19, v160
	v_add_u32_e32 v19, 0xfffffee0, v17
	v_max3_f32 v18, v18, v2, v3
	v_cndmask_b32_e32 v4, v208, v4, vcc
	v_cmp_le_i32_e32 vcc, v19, v160
	v_add_u32_e32 v19, 0xfffffef0, v17
	s_nop 0
	v_cndmask_b32_e32 v5, v208, v5, vcc
	v_cmp_le_i32_e32 vcc, v19, v160
	v_add_u32_e32 v19, 0xffffff00, v17
	v_max3_f32 v18, v18, v4, v5
	v_cndmask_b32_e32 v6, v208, v6, vcc
	v_cmp_le_i32_e32 vcc, v19, v160
	v_add_u32_e32 v19, 0xffffff50, v17
	s_nop 0
	v_cndmask_b32_e32 v7, v208, v7, vcc
	v_cmp_le_i32_e32 vcc, v19, v160
	v_add_u32_e32 v19, 0xffffff60, v17
	v_max3_f32 v18, v18, v6, v7
	v_cndmask_b32_e32 v8, v208, v8, vcc
	v_cmp_le_i32_e32 vcc, v19, v160
	v_add_u32_e32 v19, 0xffffff70, v17
	s_nop 0
	v_cndmask_b32_e32 v9, v208, v9, vcc
	v_cmp_le_i32_e32 vcc, v19, v160
	v_add_u32_e32 v19, 0xffffff80, v17
	v_max3_f32 v18, v18, v8, v9
	v_cndmask_b32_e32 v10, v208, v10, vcc
	v_cmp_le_i32_e32 vcc, v19, v160
	v_subrev_u32_e32 v19, 48, v17
	s_nop 0
	v_cndmask_b32_e32 v11, v208, v11, vcc
	v_cmp_le_i32_e32 vcc, v19, v160
	v_subrev_u32_e32 v19, 32, v17
	v_max3_f32 v18, v18, v10, v11
	v_cndmask_b32_e32 v12, v208, v12, vcc
	v_cmp_le_i32_e32 vcc, v19, v160
	v_add_u32_e32 v19, -16, v17
	s_nop 0
	v_cndmask_b32_e32 v13, v208, v13, vcc
	v_cmp_le_i32_e32 vcc, v19, v160
	v_max3_f32 v18, v18, v12, v13
	s_nop 0
	v_cndmask_b32_e32 v14, v208, v14, vcc
	v_cmp_le_i32_e32 vcc, v17, v160
	v_add_u32_e32 v17, 0x200, v17
	s_nop 0
	v_cndmask_b32_e32 v15, v208, v15, vcc
	v_max3_f32 v18, v18, v14, v15
	v_mov_b32_e32 v19, v18
	v_mov_b32_e32 v20, v18
	s_nop 1
	v_permlane32_swap_b32_e32 v19, v20
	v_cndmask_b32_e64 v19, v19, v20, s[36:37]
	v_mov_b32_e32 v20, v54
	v_max3_f32 v54, v20, v18, v19
	v_cmp_lt_f32_e32 vcc, s16, v0
	v_sub_f32_e32 v0, v0, v54
	v_exp_f32_e32 v0, v0
	v_sub_f32_e32 v18, v20, v54
	v_add_f32_e32 v0, 0, v0
	v_cndmask_b32_e32 v0, 0, v0, vcc
	v_cmp_lt_f32_e32 vcc, s16, v1
	v_sub_f32_e32 v1, v1, v54
	v_exp_f32_e32 v1, v1
	s_nop 0
	v_cndmask_b32_e32 v1, 0, v1, vcc
	v_add_f32_e32 v0, v1, v0
	v_sub_f32_e32 v1, v2, v54
	v_exp_f32_e32 v1, v1
	v_cmp_lt_f32_e32 vcc, s16, v2
	s_nop 1
	v_cndmask_b32_e32 v1, 0, v1, vcc
	v_add_f32_e32 v0, v1, v0
	v_sub_f32_e32 v1, v3, v54
	v_exp_f32_e32 v1, v1
	v_cmp_lt_f32_e32 vcc, s16, v3
	s_nop 1
	v_cndmask_b32_e32 v1, 0, v1, vcc
	v_add_f32_e32 v0, v1, v0
	v_sub_f32_e32 v1, v4, v54
	v_exp_f32_e32 v1, v1
	v_cmp_lt_f32_e32 vcc, s16, v4
	s_nop 1
	v_cndmask_b32_e32 v1, 0, v1, vcc
	v_add_f32_e32 v0, v1, v0
	v_sub_f32_e32 v1, v5, v54
	v_exp_f32_e32 v1, v1
	v_cmp_lt_f32_e32 vcc, s16, v5
	s_nop 1
	v_cndmask_b32_e32 v1, 0, v1, vcc
	v_add_f32_e32 v0, v1, v0
	v_sub_f32_e32 v1, v6, v54
	v_exp_f32_e32 v1, v1
	v_cmp_lt_f32_e32 vcc, s16, v6
	s_nop 1
	v_cndmask_b32_e32 v1, 0, v1, vcc
	v_add_f32_e32 v0, v1, v0
	v_sub_f32_e32 v1, v7, v54
	v_exp_f32_e32 v1, v1
	v_cmp_lt_f32_e32 vcc, s16, v7
	s_nop 1
	v_cndmask_b32_e32 v1, 0, v1, vcc
	v_add_f32_e32 v0, v1, v0
	v_sub_f32_e32 v1, v8, v54
	v_exp_f32_e32 v1, v1
	v_cmp_lt_f32_e32 vcc, s16, v8
	s_nop 1
	v_cndmask_b32_e32 v1, 0, v1, vcc
	v_add_f32_e32 v0, v1, v0
	v_sub_f32_e32 v1, v9, v54
	v_exp_f32_e32 v1, v1
	v_cmp_lt_f32_e32 vcc, s16, v9
	s_nop 1
	v_cndmask_b32_e32 v1, 0, v1, vcc
	v_add_f32_e32 v0, v1, v0
	v_sub_f32_e32 v1, v10, v54
	v_exp_f32_e32 v1, v1
	v_cmp_lt_f32_e32 vcc, s16, v10
	s_nop 1
	v_cndmask_b32_e32 v1, 0, v1, vcc
	v_add_f32_e32 v0, v1, v0
	v_sub_f32_e32 v1, v11, v54
	v_exp_f32_e32 v1, v1
	v_cmp_lt_f32_e32 vcc, s16, v11
	s_nop 1
	v_cndmask_b32_e32 v1, 0, v1, vcc
	v_add_f32_e32 v0, v1, v0
	v_sub_f32_e32 v1, v12, v54
	v_exp_f32_e32 v1, v1
	v_cmp_lt_f32_e32 vcc, s16, v12
	s_nop 1
	v_cndmask_b32_e32 v1, 0, v1, vcc
	v_add_f32_e32 v0, v1, v0
	v_sub_f32_e32 v1, v13, v54
	v_exp_f32_e32 v1, v1
	v_cmp_lt_f32_e32 vcc, s16, v13
	s_nop 1
	v_cndmask_b32_e32 v1, 0, v1, vcc
	v_add_f32_e32 v0, v1, v0
	v_sub_f32_e32 v1, v14, v54
	v_exp_f32_e32 v1, v1
	v_cmp_lt_f32_e32 vcc, s16, v14
	s_nop 1
	v_cndmask_b32_e32 v1, 0, v1, vcc
	v_add_f32_e32 v0, v1, v0
	v_sub_f32_e32 v1, v15, v54
	v_exp_f32_e32 v1, v1
	v_cmp_lt_f32_e32 vcc, s16, v15
	s_nop 1
	v_cndmask_b32_e32 v1, 0, v1, vcc
	v_add_f32_e32 v0, v1, v0
	v_exp_f32_e32 v1, v18
	v_mov_b32_e32 v2, v0
	v_mov_b32_e32 v3, v0
	s_nop 1
	v_permlane32_swap_b32_e32 v2, v3
	v_add_f32_e32 v0, v2, v3
	v_fmac_f32_e32 v0, v30, v1
	s_cbranch_scc0 .LBB0_513
	v_div_scale_f32 v1, s[10:11], v0, v0, 1.0
	v_rcp_f32_e32 v2, v1
	v_bfe_u32 v50, v86, 2, 2
	s_movk_i32 s1, 0x240
	v_lshlrev_b32_e32 v167, 2, v120
	v_fma_f32 v3, -v1, v2, 1.0
	v_fmac_f32_e32 v2, v3, v2
	v_div_scale_f32 v3, vcc, 1.0, v0, 1.0
	v_mul_f32_e32 v4, v3, v2
	v_fma_f32 v5, -v1, v4, v3
	v_fmac_f32_e32 v4, v5, v2
	v_fma_f32 v1, -v1, v4, v3
	v_div_fmas_f32 v1, v1, v2, v4
	v_div_fixup_f32 v1, v1, v0, 1.0
	v_cmp_lt_f32_e32 vcc, 0, v0
	v_lshlrev_b32_e32 v0, 1, v88
	v_and_b32_e32 v171, 32, v0
	v_lshlrev_b32_e32 v0, 3, v88
	v_and_b32_e32 v186, 24, v0
	v_mul_u32_u24_e32 v0, 0x90, v50
	v_mad_u32_u24 v0, v120, s1, v0
	v_readlane_b32 s1, v254, 51
	v_mov_b32_e32 v58, 0
	v_cndmask_b32_e32 v48, 0, v1, vcc
	v_add3_u32 v55, v0, v171, v186
	v_add_u32_e32 v0, s1, v64
	v_mov_b32_e32 v51, v160
	v_mov_b32_e32 v49, v48
	v_lshl_or_b32 v57, v0, 8, v167
	v_mov_b32_e32 v0, 0
	v_mov_b32_e32 v1, v58
	v_mov_b32_e32 v2, v58
	v_mov_b32_e32 v3, v58
	v_mov_b32_e32 v4, v58
	v_mov_b32_e32 v5, v58
	v_mov_b32_e32 v6, v58
	v_mov_b32_e32 v7, v58
	v_mov_b32_e32 v8, v58
	v_mov_b32_e32 v9, v58
	v_mov_b32_e32 v10, v58
	v_mov_b32_e32 v11, v58
	v_mov_b32_e32 v12, v58
	v_mov_b32_e32 v13, v58
	v_mov_b32_e32 v14, v58
	v_mov_b32_e32 v15, v58
	v_mov_b32_e32 v16, 0
	v_mov_b32_e32 v17, v58
	v_mov_b32_e32 v18, v58
	v_mov_b32_e32 v19, v58
	v_mov_b32_e32 v20, v58
	v_mov_b32_e32 v21, v58
	v_mov_b32_e32 v22, v58
	v_mov_b32_e32 v23, v58
	v_mov_b32_e32 v24, v58
	v_mov_b32_e32 v25, v58
	v_mov_b32_e32 v26, v58
	v_mov_b32_e32 v27, v58
	v_mov_b32_e32 v28, v58
	v_mov_b32_e32 v29, v58
	v_mov_b32_e32 v30, v58
	v_mov_b32_e32 v31, v58

; template <int MODE, bool PRE = false> ...
;     ...
;         for (int sub = 0; sub < 2; ++sub) {
;             const int kbase = 64 * kt + 32 * sub;
;             if (kbase > q0w + 31) continue;
;             if (MODE == MODE_NWIN && kbase + 31 <= q0w - 512) continue;
;             bool full = (kbase + 31 <= q0w);
;             if (MODE == MODE_NWIN) full = full && (kbase > q0w + 31 - 512);
;             bool lsel = true;
;             if (MODE == MODE_MOBA) lsel = ((sel >> (kbase >> 8)) & 1ull) != 0ull;
;             if (MODE == MODE_NSEL) lsel = ((sel >> kt) & 1ull) != 0ull;
;             const unsigned long long selb = __builtin_amdgcn_ballot_w64(lsel);
;             if (selb == 0ull) continue;
;             int mm; unsigned vm;
;             if (full) { mm = (selb == ~0ull) ? 0 : 1; vm = lsel ? 1u : 0u; }
;             else { mm = 2; vm = 0;
; #pragma unroll
;                 for (int i = 0; i < 16; ++i) { const int kidx = kbase + (i & 3) + 8 * (i >> 2) + 4 * h; bool ok = kidx <= qpos; if (MODE == MODE_NWIN) ok = ok && (kidx > qpos - 512); vm |= ok ? (1u << i) : 0u; }
;                 if (!lsel) vm = 0;
;                 if (__builtin_amdgcn_ballot_w64(vm != 0) == 0ull) continue; }
.LBB0_703:
	s_add_i32 s0, s10, s62
	s_cmp_gt_u32 s0, s58
	s_cbranch_scc1 .LBB0_702
	s_mul_i32 s1, s10, 0x4800
	s_lshl_b32 s11, s0, 6
	s_add_i32 s64, s63, s1
	s_or_b32 s10, s11, 63
	s_cmp_le_i32 s10, s59
	s_cselect_b64 s[52:53], -1, 0
	s_cmp_gt_i32 s11, s57
	s_cselect_b64 s[0:1], -1, 0
	s_and_b64 s[48:49], s[52:53], s[0:1]
	s_and_b64 vcc, exec, s[48:49]
	s_cbranch_vccnz .LBB0_710
	v_mov_b64_e32 v[94:95], v[30:31]
	v_add_u32_e32 v48, s64, v168
	s_waitcnt lgkmcnt(4)
	v_add3_u32 v128, s64, v171, v186
	s_cmp_le_i32 s11, s25
	v_mov_b32_e32 v130, v193
	v_mov_b32_e32 v129, v184
	v_mov_b64_e32 v[92:93], v[28:29]
	v_mov_b64_e32 v[90:91], v[26:27]
	v_mov_b64_e32 v[88:89], v[24:25]
	v_mov_b64_e32 v[86:87], v[22:23]
	v_mov_b64_e32 v[84:85], v[20:21]
	v_mov_b64_e32 v[82:83], v[18:19]
	v_mov_b64_e32 v[80:81], v[16:17]
	v_mov_b64_e32 v[78:79], v[14:15]
	v_mov_b64_e32 v[76:77], v[12:13]
	v_mov_b64_e32 v[74:75], v[10:11]
	v_mov_b64_e32 v[72:73], v[8:9]
	v_mov_b64_e32 v[70:71], v[6:7]
	v_mov_b64_e32 v[68:69], v[4:5]
	v_mov_b64_e32 v[66:67], v[2:3]
	v_mov_b64_e32 v[64:65], v[0:1]
	s_cbranch_scc0 .LBB0_744
	s_or_b32 s24, s11, 31
	s_cmp_le_i32 s24, s60
	s_cbranch_scc1 .LBB0_744
	s_cmp_eq_u64 exec, 0
	s_cbranch_scc1 .LBB0_744
	s_cmp_le_i32 s24, s59
	s_cselect_b64 s[48:49], -1, 0
	s_and_b64 s[0:1], s[48:49], s[0:1]
	s_and_b64 vcc, exec, s[0:1]
	s_cbranch_vccnz .LBB0_730
	v_or_b32_e32 v32, s11, v167
	v_cmp_le_i32_e32 vcc, v32, v160
	v_cmp_gt_i32_e64 s[0:1], v32, v165
	s_and_b64 s[0:1], vcc, s[0:1]
	v_cmp_lt_i32_e32 vcc, v32, v160
	v_cndmask_b32_e64 v33, 0, 1, s[0:1]
	v_cmp_ge_i32_e64 s[0:1], v32, v165
	s_and_b64 s[0:1], vcc, s[0:1]
	v_or_b32_e32 v35, 3, v32
	v_cndmask_b32_e64 v34, 0, 2, s[0:1]
	v_or_b32_e32 v33, v34, v33
	v_or_b32_e32 v34, 2, v32
	v_cmp_le_i32_e32 vcc, v34, v160
	v_cmp_gt_i32_e64 s[0:1], v34, v165
	s_and_b64 s[0:1], vcc, s[0:1]
	v_cmp_le_i32_e32 vcc, v35, v160
	v_cndmask_b32_e64 v34, 0, 4, s[0:1]
	v_cmp_gt_i32_e64 s[0:1], v35, v165
	s_and_b64 s[0:1], vcc, s[0:1]
	s_nop 0
	v_cndmask_b32_e64 v35, 0, 8, s[0:1]
	v_or3_b32 v33, v33, v34, v35
	v_or_b32_e32 v34, 8, v32
	v_cmp_le_i32_e32 vcc, v34, v160
	v_cmp_gt_i32_e64 s[0:1], v34, v165
	s_and_b64 s[0:1], vcc, s[0:1]
	v_or_b32_e32 v35, 9, v32
	v_cndmask_b32_e64 v34, 0, 16, s[0:1]
	v_cmp_le_i32_e32 vcc, v35, v160
	v_cmp_gt_i32_e64 s[0:1], v35, v165
	s_and_b64 s[0:1], vcc, s[0:1]
	s_nop 0
	v_cndmask_b32_e64 v35, 0, 32, s[0:1]
	v_or3_b32 v33, v33, v34, v35
	v_or_b32_e32 v34, 10, v32
	v_cmp_le_i32_e32 vcc, v34, v160
	v_cmp_gt_i32_e64 s[0:1], v34, v165
	s_and_b64 s[0:1], vcc, s[0:1]
	v_or_b32_e32 v35, 11, v32
	v_cndmask_b32_e64 v34, 0, 64, s[0:1]
	v_cmp_le_i32_e32 vcc, v35, v160
	v_cmp_gt_i32_e64 s[0:1], v35, v165
	s_and_b64 vcc, vcc, s[0:1]
	v_cndmask_b32_e32 v35, 0, v196, vcc
	v_or3_b32 v33, v33, v34, v35
	v_or_b32_e32 v34, 16, v32
	v_cmp_le_i32_e32 vcc, v34, v160
	v_cmp_gt_i32_e64 s[0:1], v34, v165
	s_and_b64 vcc, vcc, s[0:1]
	v_or_b32_e32 v35, 17, v32
	v_cndmask_b32_e32 v34, 0, v197, vcc
	v_cmp_le_i32_e32 vcc, v35, v160
	v_cmp_gt_i32_e64 s[0:1], v35, v165
	s_and_b64 vcc, vcc, s[0:1]
	v_cndmask_b32_e32 v35, 0, v198, vcc
	v_or3_b32 v33, v33, v34, v35
	v_or_b32_e32 v34, 18, v32
	v_cmp_le_i32_e32 vcc, v34, v160
	v_cmp_gt_i32_e64 s[0:1], v34, v165
	s_and_b64 vcc, vcc, s[0:1]
	v_or_b32_e32 v35, 19, v32
	v_cndmask_b32_e32 v34, 0, v199, vcc
	v_cmp_le_i32_e32 vcc, v35, v160
	v_cmp_gt_i32_e64 s[0:1], v35, v165
	s_and_b64 vcc, vcc, s[0:1]
	v_cndmask_b32_e32 v35, 0, v200, vcc
	v_or3_b32 v33, v33, v34, v35
	v_or_b32_e32 v34, 24, v32
	v_cmp_le_i32_e32 vcc, v34, v160
	v_cmp_gt_i32_e64 s[0:1], v34, v165
	s_and_b64 vcc, vcc, s[0:1]
	v_or_b32_e32 v35, 25, v32
	v_cndmask_b32_e32 v34, 0, v201, vcc
	v_cmp_le_i32_e32 vcc, v35, v160
	v_cmp_gt_i32_e64 s[0:1], v35, v165
	s_and_b64 vcc, vcc, s[0:1]
	v_cndmask_b32_e32 v35, 0, v202, vcc
	v_or3_b32 v33, v33, v34, v35
	v_or_b32_e32 v34, 26, v32
	v_cmp_le_i32_e32 vcc, v34, v160
	v_cmp_gt_i32_e64 s[0:1], v34, v165
	s_and_b64 vcc, vcc, s[0:1]
	v_or_b32_e32 v32, 27, v32
	v_cndmask_b32_e32 v34, 0, v203, vcc
	v_cmp_le_i32_e32 vcc, v32, v160
	v_cmp_gt_i32_e64 s[0:1], v32, v165
	s_and_b64 vcc, vcc, s[0:1]
	v_cndmask_b32_e32 v32, 0, v204, vcc
	v_or3_b32 v135, v33, v34, v32
	v_cmp_ne_u32_e32 vcc, 0, v135
	s_cmp_lg_u64 vcc, 0
	s_cselect_b64 s[0:1], -1, 0
	s_mov_b32 s24, 2
	s_cbranch_execz .LBB0_731
	s_branch .LBB0_732

; DI void diff_unit(const Params& P, int l, LAS char* lds, int b, int hd, int qb, int tid, int wave, int lane) {
;     ...
;     const float* lp = P.in[5] + (size_t)l * 4 * 32;
;     float s01 = (lane < 32) ? lp[lane] * lp[32 + lane] : 0.f, s23 = (lane < 32) ? lp[64 + lane] * lp[96 + lane] : 0.f;
;     s01 = wave_sum(s01, lane); s23 = wave_sum(s23, lane);
;     float lf = (float)l; asm volatile("" : "+v"(lf));
;     const float lam_init = 0.8f - 0.6f * expf(-0.3f * lf);
;     const float lam = expf(s01) - expf(s23) + lam_init;
;     const float i1 = 1.0f / l1, i2 = lam / l2;
;     float ss = 0.f;
; #pragma unroll
;     for (int dt = 0; dt < 2; ++dt)
; #pragma unroll
;         for (int i = 0; i < 16; ++i) { const float v = o1[dt][i] * i1 - o2[dt][i] * i2; o1[dt][i] = v; ss += v * v; }
.LBB0_774:
	s_or_b64 exec, exec, s[0:1]
	v_xor_b32_e32 v35, 4, v33
	ds_bpermute_b32 v36, v35, v34
	ds_bpermute_b32 v35, v35, v32
	s_mov_b32 s0, 0x3fb8aa3b
	s_mov_b32 s1, 0xc2ce8ed0
	s_mov_b32 s10, 0x42b17218
	s_waitcnt lgkmcnt(1)
	v_add_f32_e32 v34, v34, v36
	v_xor_b32_e32 v36, 8, v33
	s_waitcnt lgkmcnt(0)
	v_add_f32_e32 v32, v32, v35
	ds_bpermute_b32 v37, v36, v34
	ds_bpermute_b32 v35, v36, v32
	v_lshlrev_b32_e32 v45, 2, v214
	v_add_u32_e32 v168, 0x8000, v213
	s_waitcnt lgkmcnt(1)
	v_add_f32_e32 v34, v34, v37
	v_xor_b32_e32 v37, 16, v33
	s_waitcnt lgkmcnt(0)
	v_add_f32_e32 v32, v32, v35
	ds_bpermute_b32 v38, v37, v34
	ds_bpermute_b32 v35, v37, v32
	s_waitcnt lgkmcnt(1)
	v_add_f32_e32 v34, v34, v38
	v_xor_b32_e32 v38, 32, v33
	s_waitcnt lgkmcnt(0)
	v_add_f32_e32 v32, v32, v35
	ds_bpermute_b32 v39, v38, v34
	ds_bpermute_b32 v35, v38, v32
	v_xor_b32_e32 v33, 64, v33
	s_waitcnt lgkmcnt(1)
	v_add_f32_e32 v34, v34, v39
	s_waitcnt lgkmcnt(0)
	v_add_f32_e32 v32, v32, v35
	ds_bpermute_b32 v39, v33, v34
	ds_bpermute_b32 v33, v33, v32
	s_waitcnt lgkmcnt(1)
	v_add_f32_e32 v34, v34, v39
	s_waitcnt lgkmcnt(0)
	v_add_f32_e32 v32, v32, v33
	v_mov_b32_e32 v33, v32
	v_mov_b32_e32 v35, v32
	s_nop 1
	v_permlane32_swap_b32_e32 v33, v35
	v_add_f32_e32 v33, v33, v35
	v_mov_b32_e32 v32, v212
	v_mov_b32_e32 v39, v34
	v_mul_f32_e32 v32, 0xbe99999a, v32
	v_mul_f32_e32 v35, 0x3fb8aa3b, v32
	v_fma_f32 v36, v32, s0, -v35
	v_rndne_f32_e32 v37, v35
	v_fmac_f32_e32 v36, 0x32a5705f, v32
	v_sub_f32_e32 v35, v35, v37
	v_add_f32_e32 v35, v35, v36
	v_exp_f32_e32 v35, v35
	v_cvt_i32_f32_e32 v36, v37
	v_mov_b32_e32 v40, v34
	s_nop 1
	v_permlane32_swap_b32_e32 v39, v40
	v_cndmask_b32_e64 v39, v39, v40, s[36:37]
	v_ldexp_f32 v35, v35, v36
	v_cmp_ngt_f32_e32 vcc, s1, v32
	v_add_f32_e32 v34, v34, v39
	s_nop 0
	v_cndmask_b32_e32 v35, 0, v35, vcc
	v_cmp_nlt_f32_e32 vcc, s10, v32
	s_nop 1
	v_cndmask_b32_e32 v32, v210, v35, vcc
	v_mul_f32_e32 v35, 0x3fb8aa3b, v34
	v_fma_f32 v36, v34, s0, -v35
	v_rndne_f32_e32 v37, v35
	v_fmac_f32_e32 v36, 0x32a5705f, v34
	v_sub_f32_e32 v35, v35, v37
	v_add_f32_e32 v35, v35, v36
	v_exp_f32_e32 v35, v35
	v_cvt_i32_f32_e32 v36, v37
	v_cmp_ngt_f32_e32 vcc, s1, v34
	v_mul_f32_e32 v32, 0x3f19999a, v32
	v_ldexp_f32 v35, v35, v36
	v_cndmask_b32_e32 v35, 0, v35, vcc
	v_cmp_nlt_f32_e32 vcc, s10, v34
	v_mul_f32_e32 v34, 0x3fb8aa3b, v33
	v_rndne_f32_e32 v36, v34
	v_cndmask_b32_e32 v171, v210, v35, vcc
	v_fma_f32 v35, v33, s0, -v34
	v_fmac_f32_e32 v35, 0x32a5705f, v33
	v_sub_f32_e32 v34, v34, v36
	v_add_f32_e32 v34, v34, v35
	v_exp_f32_e32 v34, v34
	v_cvt_i32_f32_e32 v35, v36
	v_cmp_ngt_f32_e32 vcc, s1, v33
	v_ldexp_f32 v34, v34, v35
	s_nop 0
	v_cndmask_b32_e32 v34, 0, v34, vcc
	v_cmp_nlt_f32_e32 vcc, s10, v33
	s_nop 1
	v_cndmask_b32_e32 v33, v210, v34, vcc
	v_div_scale_f32 v34, s[0:1], v186, v186, 1.0
	v_rcp_f32_e32 v35, v34
	v_pk_add_f32 v[32:33], v[170:171], v[32:33] neg_lo:[0,1] neg_hi:[0,1]
	v_fma_f32 v36, -v34, v35, 1.0
	v_fmac_f32_e32 v35, v36, v35
	v_div_scale_f32 v36, vcc, 1.0, v186, 1.0
	v_mul_f32_e32 v37, v36, v35
	v_fma_f32 v38, -v34, v37, v36
	v_fmac_f32_e32 v37, v38, v35
	v_fma_f32 v34, -v34, v37, v36
	v_add_f32_e32 v33, v32, v33
	v_div_fmas_f32 v34, v34, v35, v37
	v_div_fixup_f32 v44, v34, v186, 1.0
	v_div_scale_f32 v34, s[0:1], v217, v217, v33
	v_rcp_f32_e32 v35, v34
	v_sub_f32_e32 v100, 1.0, v32
	v_fma_f32 v36, -v34, v35, 1.0
	v_fmac_f32_e32 v35, v36, v35
	v_div_scale_f32 v36, vcc, v33, v217, v33
	v_mul_f32_e32 v37, v36, v35
	v_fma_f32 v38, -v34, v37, v36
	v_fmac_f32_e32 v37, v38, v35
	v_fma_f32 v34, -v34, v37, v36
	v_div_fmas_f32 v34, v34, v35, v37
	v_div_fixup_f32 v46, v34, v217, v33
	v_pk_mul_f32 v[32:33], v[80:81], v[46:47] op_sel_hi:[1,0]
	v_pk_mul_f32 v[72:73], v[72:73], v[46:47] op_sel_hi:[1,0]
	v_pk_fma_f32 v[36:37], v[44:45], v[16:17], v[32:33] op_sel_hi:[0,1,1] neg_lo:[0,0,1] neg_hi:[0,0,1]
	v_pk_mul_f32 v[16:17], v[82:83], v[46:47] op_sel_hi:[1,0]
	v_pk_mul_f32 v[68:69], v[68:69], v[46:47] op_sel_hi:[1,0]
	v_pk_fma_f32 v[38:39], v[44:45], v[18:19], v[16:17] op_sel_hi:[0,1,1] neg_lo:[0,0,1] neg_hi:[0,0,1]
	v_pk_mul_f32 v[16:17], v[84:85], v[46:47] op_sel_hi:[1,0]
	v_pk_fma_f32 v[72:73], v[44:45], v[8:9], v[72:73] op_sel_hi:[0,1,1] neg_lo:[0,0,1] neg_hi:[0,0,1]
	v_pk_fma_f32 v[40:41], v[44:45], v[20:21], v[16:17] op_sel_hi:[0,1,1] neg_lo:[0,0,1] neg_hi:[0,0,1]
	v_pk_mul_f32 v[20:21], v[86:87], v[46:47] op_sel_hi:[1,0]
	v_pk_mul_f32 v[8:9], v[70:71], v[46:47] op_sel_hi:[1,0]
	v_pk_fma_f32 v[42:43], v[44:45], v[22:23], v[20:21] op_sel_hi:[0,1,1] neg_lo:[0,0,1] neg_hi:[0,0,1]
	v_pk_mul_f32 v[20:21], v[88:89], v[46:47] op_sel_hi:[1,0]
	v_pk_fma_f32 v[68:69], v[44:45], v[4:5], v[68:69] op_sel_hi:[0,1,1] neg_lo:[0,0,1] neg_hi:[0,0,1]
	v_pk_mul_f32 v[4:5], v[66:67], v[46:47] op_sel_hi:[1,0]
	v_pk_fma_f32 v[56:57], v[44:45], v[24:25], v[20:21] op_sel_hi:[0,1,1] neg_lo:[0,0,1] neg_hi:[0,0,1]
	v_pk_mul_f32 v[24:25], v[90:91], v[46:47] op_sel_hi:[1,0]
	v_pk_fma_f32 v[70:71], v[44:45], v[6:7], v[8:9] op_sel_hi:[0,1,1] neg_lo:[0,0,1] neg_hi:[0,0,1]
	global_load_dwordx4 v[6:9], v45, s[34:35] offset:32
	v_pk_fma_f32 v[66:67], v[44:45], v[2:3], v[4:5] op_sel_hi:[0,1,1] neg_lo:[0,0,1] neg_hi:[0,0,1]
	global_load_dwordx4 v[2:5], v45, s[34:35]
	v_pk_fma_f32 v[60:61], v[44:45], v[26:27], v[24:25] op_sel_hi:[0,1,1] neg_lo:[0,0,1] neg_hi:[0,0,1]
	v_pk_mul_f32 v[24:25], v[92:93], v[46:47] op_sel_hi:[1,0]
	v_pk_mul_f32 v[76:77], v[76:77], v[46:47] op_sel_hi:[1,0]
	v_pk_fma_f32 v[80:81], v[44:45], v[28:29], v[24:25] op_sel_hi:[0,1,1] neg_lo:[0,0,1] neg_hi:[0,0,1]
	v_pk_mul_f32 v[28:29], v[94:95], v[46:47] op_sel_hi:[1,0]
; DI void diff_unit(const Params& P, int l, LAS char* lds, int b, int hd, int qb, int tid, int wave, int lane) {
;     ...
;     const float i1 = 1.0f / l1, i2 = lam / l2;
;     float ss = 0.f;
; #pragma unroll
;     for (int dt = 0; dt < 2; ++dt)
; #pragma unroll
;         for (int i = 0; i < 16; ++i) { const float v = o1[dt][i] * i1 - o2[dt][i] * i2; o1[dt][i] = v; ss += v * v; }
;     ss += shx32(ss, lane);
;     const float rstd = (1.0f - lam_init) / sqrtf(ss * (1.0f / 64.0f) + RMS_EPS);
;     const float* sg = P.in[6] + (size_t)l * 64;
; #pragma unroll
;     for (int dt = 0; dt < 2; ++dt)
; #pragma unroll
;         for (int i = 0; i < 16; ++i) o1[dt][i] = o1[dt][i] * rstd * sg[32 * dt + (i & 3) + 8 * (i >> 2) + 4 * h];
;     store_o((bf16_t*)(P.ws + WS_O) + ((size_t)1 * TOK + (size_t)b * SEQ + qpos) * 256 + 64 * hd, o1, h);
	v_pk_fma_f32 v[76:77], v[44:45], v[12:13], v[76:77] op_sel_hi:[0,1,1] neg_lo:[0,0,1] neg_hi:[0,0,1]
	v_pk_fma_f32 v[84:85], v[44:45], v[30:31], v[28:29] op_sel_hi:[0,1,1] neg_lo:[0,0,1] neg_hi:[0,0,1]
	v_pk_mul_f32 v[28:29], v[78:79], v[46:47] op_sel_hi:[1,0]
	v_pk_mul_f32 v[12:13], v[74:75], v[46:47] op_sel_hi:[1,0]
	v_pk_fma_f32 v[14:15], v[44:45], v[14:15], v[28:29] op_sel_hi:[0,1,1] neg_lo:[0,0,1] neg_hi:[0,0,1]
	global_load_dwordx4 v[28:31], v45, s[34:35] offset:96
	v_pk_fma_f32 v[74:75], v[44:45], v[10:11], v[12:13] op_sel_hi:[0,1,1] neg_lo:[0,0,1] neg_hi:[0,0,1]
	global_load_dwordx4 v[10:13], v45, s[34:35] offset:64
	v_pk_mul_f32 v[46:47], v[64:65], v[46:47] op_sel_hi:[1,0]
	global_load_dwordx4 v[32:35], v45, s[34:35] offset:128
	global_load_dwordx4 v[16:19], v45, s[34:35] offset:160
	v_pk_fma_f32 v[0:1], v[44:45], v[0:1], v[46:47] op_sel_hi:[0,1,1] neg_lo:[0,0,1] neg_hi:[0,0,1]
	global_load_dwordx4 v[20:23], v45, s[34:35] offset:192
	global_load_dwordx4 v[24:27], v45, s[34:35] offset:224
	v_pk_mul_f32 v[44:45], v[0:1], v[0:1]
	v_pk_mul_f32 v[98:99], v[66:67], v[66:67]
	v_add_f32_e32 v44, v44, v45
	v_add_f32_e32 v44, v98, v44
	v_pk_mul_f32 v[96:97], v[68:69], v[68:69]
	v_add_f32_e32 v44, v99, v44
	v_add_f32_e32 v44, v96, v44
	v_pk_mul_f32 v[94:95], v[70:71], v[70:71]
	v_add_f32_e32 v44, v97, v44
	v_add_f32_e32 v44, v94, v44
	v_pk_mul_f32 v[92:93], v[72:73], v[72:73]
	v_add_f32_e32 v44, v95, v44
	v_add_f32_e32 v44, v92, v44
	v_pk_mul_f32 v[90:91], v[74:75], v[74:75]
	v_add_f32_e32 v44, v93, v44
	v_add_f32_e32 v44, v90, v44
	v_pk_mul_f32 v[88:89], v[76:77], v[76:77]
	v_add_f32_e32 v44, v91, v44
	v_add_f32_e32 v44, v88, v44
	v_pk_mul_f32 v[78:79], v[14:15], v[14:15]
	v_add_f32_e32 v44, v89, v44
	v_add_f32_e32 v44, v78, v44
	v_pk_mul_f32 v[48:49], v[36:37], v[36:37]
	v_add_f32_e32 v44, v79, v44
	v_add_f32_e32 v44, v48, v44
	v_pk_mul_f32 v[50:51], v[38:39], v[38:39]
	v_add_f32_e32 v44, v49, v44
	v_add_f32_e32 v44, v50, v44
	v_pk_mul_f32 v[52:53], v[40:41], v[40:41]
	v_add_f32_e32 v44, v51, v44
	v_add_f32_e32 v44, v52, v44
	v_pk_mul_f32 v[54:55], v[42:43], v[42:43]
	v_add_f32_e32 v44, v53, v44
	v_add_f32_e32 v44, v54, v44
	v_pk_mul_f32 v[58:59], v[56:57], v[56:57]
	v_add_f32_e32 v44, v55, v44
	v_add_f32_e32 v44, v58, v44
	v_pk_mul_f32 v[62:63], v[60:61], v[60:61]
	v_add_f32_e32 v44, v59, v44
	v_add_f32_e32 v44, v62, v44
	v_pk_mul_f32 v[82:83], v[80:81], v[80:81]
	v_add_f32_e32 v44, v63, v44
	v_add_f32_e32 v44, v82, v44
	v_pk_mul_f32 v[86:87], v[84:85], v[84:85]
	v_add_f32_e32 v44, v83, v44
	v_add_f32_e32 v44, v86, v44
	v_add_f32_e32 v44, v87, v44
	v_mov_b32_e32 v45, v44
	v_mov_b32_e32 v46, v44
	s_nop 1
	v_permlane32_swap_b32_e32 v45, v46
	v_add_f32_e32 v44, v45, v46
	v_fmamk_f32 v44, v44, 0x3c800000, v185
	v_cmp_gt_f32_e32 vcc, s83, v44
	v_mul_f32_e32 v45, 0x4f800000, v44
	s_nop 0
	v_cndmask_b32_e32 v44, v44, v45, vcc
	v_sqrt_f32_e32 v45, v44
	s_nop 0
	v_add_u32_e32 v46, -1, v45
	v_fma_f32 v47, -v46, v45, v44
	v_cmp_ge_f32_e64 s[0:1], 0, v47
	v_add_u32_e32 v47, 1, v45
	s_nop 0
	v_cndmask_b32_e64 v46, v45, v46, s[0:1]
	v_fma_f32 v45, -v47, v45, v44
	v_cmp_lt_f32_e64 s[0:1], 0, v45
	s_nop 1
	v_cndmask_b32_e64 v45, v46, v47, s[0:1]
	v_mul_f32_e32 v46, 0x37800000, v45
	v_cndmask_b32_e32 v45, v45, v46, vcc
	v_cmp_class_f32_e32 vcc, v44, v194
	s_nop 1
	v_cndmask_b32_e32 v44, v45, v44, vcc
	v_div_scale_f32 v45, s[0:1], v44, v44, v100
	v_rcp_f32_e32 v46, v45
	s_nop 0
	v_fma_f32 v47, -v45, v46, 1.0
	v_fmac_f32_e32 v46, v47, v46
	v_div_scale_f32 v47, vcc, v100, v44, v100
	v_mul_f32_e32 v48, v47, v46
	v_fma_f32 v49, -v45, v48, v47
	v_fmac_f32_e32 v48, v49, v46
	v_fma_f32 v45, -v45, v48, v47
	v_div_fmas_f32 v45, v45, v46, v48
	v_div_fixup_f32 v44, v45, v44, v100
	v_pk_mul_f32 v[0:1], v[0:1], v[44:45] op_sel_hi:[1,0]
	v_pk_mul_f32 v[14:15], v[14:15], v[44:45] op_sel_hi:[1,0]
	s_waitcnt vmcnt(6)
	v_pk_mul_f32 v[0:1], v[2:3], v[0:1]
	v_pk_mul_f32 v[2:3], v[66:67], v[44:45] op_sel_hi:[1,0]
	v_cvt_pk_bf16_f32 v0, v0, v1
	v_pk_mul_f32 v[2:3], v[4:5], v[2:3]
	v_pk_mul_f32 v[4:5], v[68:69], v[44:45] op_sel_hi:[1,0]
	v_cvt_pk_bf16_f32 v1, v2, v3
	v_pk_mul_f32 v[4:5], v[6:7], v[4:5]
	v_pk_mul_f32 v[6:7], v[70:71], v[44:45] op_sel_hi:[1,0]
	s_waitcnt vmcnt(5)
	v_pk_mul_f32 v[14:15], v[30:31], v[14:15]
	v_pk_mul_f32 v[6:7], v[8:9], v[6:7]
	v_pk_mul_f32 v[8:9], v[72:73], v[44:45] op_sel_hi:[1,0]
	v_pk_mul_f32 v[2:3], v[38:39], v[44:45] op_sel_hi:[1,0]
	s_waitcnt vmcnt(4)
	v_pk_mul_f32 v[8:9], v[10:11], v[8:9]
	v_pk_mul_f32 v[10:11], v[74:75], v[44:45] op_sel_hi:[1,0]
	s_waitcnt vmcnt(3)
	v_pk_mul_f32 v[2:3], v[34:35], v[2:3]
	v_pk_mul_f32 v[10:11], v[12:13], v[10:11]
	v_pk_mul_f32 v[12:13], v[76:77], v[44:45] op_sel_hi:[1,0]
	s_nop 0
	v_pk_mul_f32 v[12:13], v[28:29], v[12:13]
	v_lshlrev_b64 v[28:29], 9, v[168:169]
	v_lshl_add_u64 v[28:29], s[84:85], 0, v[28:29]
	v_lshl_add_u64 v[28:29], v[28:29], 0, s[22:23]
	v_lshlrev_b32_e32 v168, 1, v214
	v_lshl_add_u64 v[28:29], v[28:29], 0, v[168:169]
	global_store_dwordx2 v[28:29], v[0:1], off
	v_cvt_pk_bf16_f32 v0, v4, v5
	v_cvt_pk_bf16_f32 v1, v6, v7
	global_store_dwordx2 v[28:29], v[0:1], off offset:16
	v_cvt_pk_bf16_f32 v0, v8, v9
	v_cvt_pk_bf16_f32 v1, v10, v11
	global_store_dwordx2 v[28:29], v[0:1], off offset:32
	v_cvt_pk_bf16_f32 v0, v12, v13
	v_cvt_pk_bf16_f32 v1, v14, v15
	global_store_dwordx2 v[28:29], v[0:1], off offset:48
	v_pk_mul_f32 v[0:1], v[36:37], v[44:45] op_sel_hi:[1,0]
	v_pk_mul_f32 v[4:5], v[40:41], v[44:45] op_sel_hi:[1,0]
	v_pk_mul_f32 v[6:7], v[42:43], v[44:45] op_sel_hi:[1,0]
	v_pk_mul_f32 v[0:1], v[32:33], v[0:1]
	v_pk_mul_f32 v[8:9], v[56:57], v[44:45] op_sel_hi:[1,0]
	v_pk_mul_f32 v[10:11], v[60:61], v[44:45] op_sel_hi:[1,0]
	s_waitcnt vmcnt(6)
	v_pk_mul_f32 v[6:7], v[18:19], v[6:7]
	v_pk_mul_f32 v[4:5], v[16:17], v[4:5]
	v_cvt_pk_bf16_f32 v0, v0, v1
	v_cvt_pk_bf16_f32 v1, v2, v3
	v_pk_mul_f32 v[12:13], v[80:81], v[44:45] op_sel_hi:[1,0]
	v_pk_mul_f32 v[14:15], v[84:85], v[44:45] op_sel_hi:[1,0]
	s_waitcnt vmcnt(5)
	v_pk_mul_f32 v[10:11], v[22:23], v[10:11]
	v_pk_mul_f32 v[8:9], v[20:21], v[8:9]
	global_store_dwordx2 v[28:29], v[0:1], off offset:64
	v_cvt_pk_bf16_f32 v0, v4, v5
	v_cvt_pk_bf16_f32 v1, v6, v7
	s_waitcnt vmcnt(5)
	v_pk_mul_f32 v[14:15], v[26:27], v[14:15]
	v_pk_mul_f32 v[12:13], v[24:25], v[12:13]
	global_store_dwordx2 v[28:29], v[0:1], off offset:80
	v_cvt_pk_bf16_f32 v0, v8, v9
	v_cvt_pk_bf16_f32 v1, v10, v11
	global_store_dwordx2 v[28:29], v[0:1], off offset:96
	v_cvt_pk_bf16_f32 v0, v12, v13
	v_cvt_pk_bf16_f32 v1, v14, v15
	global_store_dwordx2 v[28:29], v[0:1], off offset:112

; #define LAS __attribute__((address_space(3)))
; DI void unpack8(const u32x4 w, float (&v)[8]) { v[0] = bflo(w.x); v[1] = bfhi(w.x); v[2] = bflo(w.y); v[3] = bfhi(w.y); v[4] = bflo(w.z); v[5] = bfhi(w.z); v[6] = bflo(w.w); v[7] = bfhi(w.w); }
; template <bool DIFFQ> DI void norm_rope_q(bf16x8 (&qf)[4], const float* g, float qs, int qpos, int h, int lane) {
;     float qv[4][8];
; #pragma unroll
;     for (int ks = 0; ks < 4; ++ks) unpack8(__builtin_bit_cast(u32x4, qf[ks]), qv[ks]);
;     float ssa = 0.f, ssb = 0.f;
; #pragma unroll
;     for (int j = 0; j < 8; ++j) { ssa += qv[0][j] * qv[0][j] + qv[1][j] * qv[1][j]; ssb += qv[2][j] * qv[2][j] + qv[3][j] * qv[3][j]; }
;     ssa += shx32(ssa, lane); ssb += shx32(ssb, lane);
;     float ra, rb;
;     if (DIFFQ) { ra = 1.0f / sqrtf(ssa * (1.0f / 32.0f) + RMS_EPS); rb = 1.0f / sqrtf(ssb * (1.0f / 32.0f) + RMS_EPS); }
; DI void diff_unit(const Params& P, int l, LAS char* lds, int b, int hd, int qb, int tid, int wave, int lane) {
;     const bf16_t* hb = (const bf16_t*)(P.ws + WS_H);
;     const int r = lane & 31, h = lane >> 5, q0w = 256 * qb + 32 * wave, qpos = q0w + r;
;     bf16x8 qf[4]; load_q(qf, hb + (size_t)(b * SEQ + qpos) * NIN + C_DFQ + 64 * hd, h);
;     Stage2 st0; flash_prefetch(st0, hb + (size_t)b * SEQ * NIN + C_DFK + 64 * hd, hb + (size_t)b * SEQ * NIN + C_DFV + 64 * hd, NIN, 0, 4 * qb + 3, tid);
;     norm_rope_q<true>(qf, P.in[3] + (size_t)l * 32, 0.17677669529663687f * LOG2E, qpos & (SEQ - 1), h, lane);
;     const bf16_t* Kg = hb + (size_t)b * SEQ * NIN + C_DFK + 64 * hd; const bf16_t* Vg = hb + (size_t)b * SEQ * NIN + C_DFV + 64 * hd;
.LBB0_776:
	s_bitcmp0_b32 s25, 0
	s_cselect_b32 s1, s2, s78
	s_add_i32 s0, s1, s0
	s_cmpk_gt_i32 s0, 0x1ff
	s_cbranch_scc1 .LBB0_775
	s_ashr_i32 s1, s0, 5
	s_sub_i32 s10, 15, s1
	s_lshl_b32 s27, s10, 8
	s_barrier
	v_mbcnt_lo_u32_b32 v47, -1, 0
	v_mbcnt_hi_u32_b32 v47, -1, v47
	s_add_i32 s27, s27, s92
	v_and_b32_e32 v46, 31, v47
	s_lshl_b32 s1, s0, 10
	v_or_b32_e32 v171, s27, v46
	s_and_b32 s1, s1, 0x7000
	s_lshl_b32 s0, s0, 6
	v_add_u32_e32 v213, s1, v171
	v_mov_b64_e32 v[0:1], s[28:29]
	s_and_b32 s0, s0, 0xc0
	v_bfe_u32 v48, v47, 5, 1
	v_mad_u64_u32 v[0:1], s[36:37], v213, s82, v[0:1]
	s_lshl_b32 s22, s0, 1
	v_lshl_add_u64 v[0:1], v[0:1], 0, s[22:23]
	v_lshlrev_b32_e32 v168, 4, v48
	v_lshl_add_u64 v[20:21], v[0:1], 0, v[168:169]
	global_load_dwordx4 v[28:31], v[20:21], off offset:1568
	global_load_dwordx4 v[36:39], v[20:21], off offset:1536
	global_load_dwordx4 v[8:11], v[20:21], off offset:1632
	v_add_u32_e32 v0, s33, v47
	v_ashrrev_i32_e32 v216, 3, v0
	s_mul_i32 s11, s1, 0x1800
	v_add_u32_e32 v24, 64, v216
	v_mad_i64_i32 v[22:23], s[0:1], v216, s18, 0
	s_add_u32 s11, s28, s11
	v_mad_i64_i32 v[24:25], s[0:1], v24, s18, 0
	v_lshlrev_b32_e32 v1, 3, v47
	s_addc_u32 s0, s29, 0
	s_mov_b64 s[70:71], s[84:85]
	v_and_b32_e32 v26, 56, v1
	s_add_u32 s84, s11, s22
	v_and_b32_e32 v16, 32, v47
	v_or_b32_e32 v22, v22, v26
	v_or_b32_e32 v24, v24, v26
	s_addc_u32 s85, s0, 0
	global_load_dwordx4 v[0:3], v16, s[86:87] offset:80
	global_load_dwordx4 v[4:7], v16, s[86:87] offset:64
	global_load_dwordx4 v[12:15], v16, s[86:87] offset:16
	s_nop 0
	global_load_dwordx4 v[16:19], v16, s[86:87]
	v_lshl_add_u64 v[26:27], v[22:23], 1, s[84:85]
	v_lshl_add_u64 v[24:25], v[24:25], 1, s[84:85]
	global_load_dwordx4 v[20:23], v[20:21], off offset:1600
	s_nop 0
	global_load_dwordx4 v[136:139], v[26:27], off offset:2048
	global_load_dwordx4 v[140:143], v[26:27], off offset:2560
	global_load_dwordx4 v[144:147], v[24:25], off offset:2048
	global_load_dwordx4 v[148:151], v[24:25], off offset:2560
	v_and_b32_e32 v215, 63, v47
	v_cmp_gt_u32_e64 s[36:37], 32, v215
	s_mov_b32 s97, s92
	s_waitcnt vmcnt(11)
	v_lshlrev_b32_e32 v24, 16, v28
	v_and_b32_e32 v25, 0xffff0000, v28
	v_lshlrev_b32_e32 v26, 16, v29
	v_and_b32_e32 v27, 0xffff0000, v29
	s_waitcnt vmcnt(10)
	v_and_b32_e32 v41, 0xffff0000, v37
	v_lshlrev_b32_e32 v40, 16, v37
	v_and_b32_e32 v35, 0xffff0000, v39
	v_lshlrev_b32_e32 v34, 16, v39
	v_and_b32_e32 v43, 0xffff0000, v36
	v_lshlrev_b32_e32 v42, 16, v36
	v_and_b32_e32 v37, 0xffff0000, v38
	v_lshlrev_b32_e32 v36, 16, v38
	v_pk_mul_f32 v[38:39], v[24:25], v[24:25]
	v_pk_mul_f32 v[44:45], v[26:27], v[26:27]
	v_pk_fma_f32 v[38:39], v[42:43], v[42:43], v[38:39]
	v_lshlrev_b32_e32 v28, 16, v30
	v_and_b32_e32 v29, 0xffff0000, v30
	v_pk_fma_f32 v[44:45], v[40:41], v[40:41], v[44:45]
	v_add_f32_e32 v33, v38, v39
	v_pk_mul_f32 v[52:53], v[28:29], v[28:29]
	v_add_f32_e32 v33, v44, v33
	v_lshlrev_b32_e32 v30, 16, v31
	v_and_b32_e32 v31, 0xffff0000, v31
	v_pk_fma_f32 v[52:53], v[36:37], v[36:37], v[52:53]
	v_add_f32_e32 v33, v45, v33
	v_pk_mul_f32 v[50:51], v[30:31], v[30:31]
	v_add_f32_e32 v33, v52, v33
	v_pk_fma_f32 v[50:51], v[34:35], v[34:35], v[50:51]
	v_add_f32_e32 v33, v53, v33
	v_add_f32_e32 v33, v50, v33
	v_add_f32_e32 v33, v51, v33
	v_mov_b32_e32 v38, v33
	v_mov_b32_e32 v39, v33
	s_nop 1
	v_permlane32_swap_b32_e32 v38, v39
	v_add_f32_e32 v33, v38, v39
	v_fmamk_f32 v33, v33, 0x3d000000, v185
	v_mul_f32_e32 v38, 0x4f800000, v33
	v_cmp_gt_f32_e32 vcc, s83, v33
	s_waitcnt vmcnt(9)
	v_lshlrev_b32_e32 v32, 16, v8
	s_waitcnt vmcnt(4)
; template <bool DIFFQ> DI void norm_rope_q(bf16x8 (&qf)[4], const float* g, float qs, int qpos, int h, int lane) {
;     ...
;     float ssa = 0.f, ssb = 0.f;
; #pragma unroll
;     for (int j = 0; j < 8; ++j) { ssa += qv[0][j] * qv[0][j] + qv[1][j] * qv[1][j]; ssb += qv[2][j] * qv[2][j] + qv[3][j] * qv[3][j]; }
;     ssa += shx32(ssa, lane); ssb += shx32(ssb, lane);
;     float ra, rb;
;     if (DIFFQ) { ra = 1.0f / sqrtf(ssa * (1.0f / 32.0f) + RMS_EPS); rb = 1.0f / sqrtf(ssb * (1.0f / 32.0f) + RMS_EPS); }
;     else { ra = rb = 1.0f / sqrtf((ssa + ssb) * (1.0f / 64.0f) + RMS_EPS); }
; #pragma unroll
;     for (int ks = 0; ks < 4; ++ks)
; #pragma unroll
;         for (int j = 0; j < 8; ++j) { const int d = 16 * ks + 8 * h + j; qv[ks][j] = qv[ks][j] * (ks < 2 ? ra : rb) * g[DIFFQ ? (d & 31) : d]; }
;     const float pos = (float)qpos;
;     if (DIFFQ) {
;         if (h == 0) {
; #pragma unroll
;             for (int mp = 0; mp < 2; ++mp)
; #pragma unroll
;                 for (int e = 0; e < 4; ++e) { float c, sn; rope_cs(pos, exp2f(-(float)e * 0.25f * LOG2_THETA), c, sn);
;                     const float a = qv[2 * mp][e], bq = qv[2 * mp][e + 4]; qv[2 * mp][e] = a * c - bq * sn; qv[2 * mp][e + 4] = bq * c + a * sn; }
;         }
	v_and_b32_e32 v61, 0xffff0000, v20
	v_cndmask_b32_e32 v38, v33, v38, vcc
	v_sqrt_f32_e32 v39, v38
	v_and_b32_e32 v33, 0xffff0000, v8
	v_lshlrev_b32_e32 v8, 16, v9
	v_and_b32_e32 v9, 0xffff0000, v9
	v_add_u32_e32 v44, -1, v39
	v_add_u32_e32 v45, 1, v39
	v_fma_f32 v49, -v44, v39, v38
	v_fma_f32 v50, -v45, v39, v38
	v_cmp_ge_f32_e64 s[0:1], 0, v49
	v_lshlrev_b32_e32 v60, 16, v20
	v_and_b32_e32 v53, 0xffff0000, v21
	v_cndmask_b32_e64 v39, v39, v44, s[0:1]
	v_cmp_lt_f32_e64 s[0:1], 0, v50
	v_pk_mul_f32 v[56:57], v[8:9], v[8:9]
	v_and_b32_e32 v55, 0xffff0000, v23
	v_cndmask_b32_e64 v39, v39, v45, s[0:1]
	v_mul_f32_e32 v44, 0x37800000, v39
	v_cndmask_b32_e32 v39, v39, v44, vcc
	v_cmp_class_f32_e32 vcc, v38, v194
	v_pk_mul_f32 v[44:45], v[32:33], v[32:33]
	v_lshlrev_b32_e32 v54, 16, v23
	v_cndmask_b32_e32 v38, v39, v38, vcc
	v_div_scale_f32 v39, s[0:1], v38, v38, 1.0
	v_rcp_f32_e32 v49, v39
	v_div_scale_f32 v50, vcc, 1.0, v38, 1.0
	v_and_b32_e32 v63, 0xffff0000, v22
	v_fma_f32 v51, -v39, v49, 1.0
	v_fmac_f32_e32 v49, v51, v49
	v_mul_f32_e32 v51, v50, v49
	v_fma_f32 v52, -v39, v51, v50
	v_fmac_f32_e32 v51, v52, v49
	v_fma_f32 v39, -v39, v51, v50
	v_div_fmas_f32 v39, v39, v49, v51
	v_div_fixup_f32 v38, v39, v38, 1.0
	v_lshlrev_b32_e32 v52, 16, v21
	v_pk_fma_f32 v[20:21], v[60:61], v[60:61], v[44:45]
	v_pk_mul_f32 v[50:51], v[38:39], v[40:41] op_sel_hi:[0,1]
	v_lshlrev_b32_e32 v40, 16, v10
	v_and_b32_e32 v41, 0xffff0000, v10
	v_pk_fma_f32 v[56:57], v[52:53], v[52:53], v[56:57]
	v_add_f32_e32 v20, v20, v21
	v_lshlrev_b32_e32 v62, 16, v22
	v_pk_mul_f32 v[22:23], v[40:41], v[40:41]
	v_add_f32_e32 v20, v56, v20
	v_lshlrev_b32_e32 v10, 16, v11
	v_and_b32_e32 v11, 0xffff0000, v11
	v_pk_fma_f32 v[22:23], v[62:63], v[62:63], v[22:23]
	v_add_f32_e32 v20, v57, v20
	v_pk_mul_f32 v[58:59], v[10:11], v[10:11]
	v_add_f32_e32 v20, v22, v20
	v_pk_fma_f32 v[58:59], v[54:55], v[54:55], v[58:59]
	v_add_f32_e32 v20, v23, v20
	v_add_f32_e32 v20, v58, v20
	v_add_f32_e32 v20, v59, v20
	v_mov_b32_e32 v21, v20
	v_mov_b32_e32 v22, v20
	s_nop 1
	v_permlane32_swap_b32_e32 v21, v22
	v_add_f32_e32 v20, v21, v22
	v_fmamk_f32 v20, v20, 0x3d000000, v185
	v_mul_f32_e32 v21, 0x4f800000, v20
	v_cmp_gt_f32_e32 vcc, s83, v20
	v_pk_mul_f32 v[42:43], v[38:39], v[42:43] op_sel_hi:[0,1]
	v_pk_mul_f32 v[22:23], v[18:19], v[50:51]
	v_cndmask_b32_e32 v39, v20, v21, vcc
	v_sqrt_f32_e32 v44, v39
	v_pk_mul_f32 v[20:21], v[38:39], v[34:35] op_sel_hi:[0,1]
	v_pk_mul_f32 v[36:37], v[38:39], v[36:37] op_sel_hi:[0,1]
	v_pk_mul_f32 v[20:21], v[14:15], v[20:21]
	v_add_u32_e32 v34, -1, v44
	v_fma_f32 v35, -v34, v44, v39
	v_cmp_ge_f32_e64 s[0:1], 0, v35
	v_add_u32_e32 v35, 1, v44
	s_nop 0
	v_cndmask_b32_e64 v34, v44, v34, s[0:1]
	v_fma_f32 v44, -v35, v44, v39
	v_cmp_lt_f32_e64 s[0:1], 0, v44
	v_pk_mul_f32 v[44:45], v[16:17], v[42:43]
	s_nop 0
	v_cndmask_b32_e64 v34, v34, v35, s[0:1]
	v_mul_f32_e32 v35, 0x37800000, v34
	v_cndmask_b32_e32 v34, v34, v35, vcc
	v_cmp_class_f32_e32 vcc, v39, v194
	s_nop 1
	v_cndmask_b32_e32 v39, v34, v39, vcc
	v_div_scale_f32 v49, s[0:1], v39, v39, 1.0
	v_rcp_f32_e32 v50, v49
	v_pk_mul_f32 v[34:35], v[12:13], v[36:37]
	v_fma_f32 v36, -v49, v50, 1.0
	v_fmac_f32_e32 v50, v36, v50
	v_div_scale_f32 v36, vcc, 1.0, v39, 1.0
	v_mul_f32_e32 v37, v36, v50
	v_fma_f32 v42, -v49, v37, v36
	v_fmac_f32_e32 v37, v42, v50
	v_fma_f32 v36, -v49, v37, v36
	v_div_fmas_f32 v36, v36, v50, v37
	v_div_fixup_f32 v42, v36, v39, 1.0
	v_pk_mul_f32 v[36:37], v[42:43], v[60:61] op_sel_hi:[0,1]
	v_pk_mul_f32 v[36:37], v[16:17], v[36:37]
	v_pk_mul_f32 v[16:17], v[42:43], v[52:53] op_sel_hi:[0,1]
	v_pk_mul_f32 v[18:19], v[18:19], v[16:17]
	v_pk_mul_f32 v[16:17], v[42:43], v[62:63] op_sel_hi:[0,1]
	v_pk_mul_f32 v[16:17], v[12:13], v[16:17]
	v_pk_mul_f32 v[12:13], v[42:43], v[54:55] op_sel_hi:[0,1]
	v_pk_mul_f32 v[12:13], v[14:15], v[12:13]
	s_and_saveexec_b64 s[0:1], s[36:37]
	s_cbranch_execz .LBB0_779
	v_and_b32_e32 v14, 0xfff, v171
	v_cvt_f32_u32_e32 v39, v14
	v_cvt_f64_u32_e32 v[14:15], v14
	v_mul_f64 v[50:51], v[14:15], s[4:5]
	v_rndne_f64_e32 v[50:51], v[50:51]
	v_fma_f64 v[14:15], v[14:15], s[4:5], -v[50:51]
	v_cvt_f32_f64_e32 v15, v[14:15]
	v_sin_f32_e32 v14, v15
	v_cos_f32_e32 v50, v15
	v_mul_f32_e32 v15, 0x3d1a08c9, v39
	v_cvt_f64_f32_e32 v[52:53], v15
	v_mul_f64 v[54:55], v[52:53], s[4:5]
	v_rndne_f64_e32 v[54:55], v[54:55]
	v_fma_f64 v[52:53], v[52:53], s[4:5], -v[54:55]
	v_cvt_f32_f64_e32 v43, v[52:53]
	v_sin_f32_e32 v15, v43
	v_cos_f32_e32 v51, v43
	v_mul_f32_e32 v43, 0x3ab95d24, v39
	v_mul_f32_e32 v39, 0x385f10c8, v39
	v_pk_mul_f32 v[52:53], v[14:15], v[34:35]
	v_pk_mul_f32 v[34:35], v[50:51], v[34:35]
	v_pk_fma_f32 v[52:53], v[50:51], v[44:45], v[52:53] neg_lo:[0,0,1] neg_hi:[0,0,1]
	v_pk_fma_f32 v[34:35], v[14:15], v[44:45], v[34:35]
	v_cvt_f64_f32_e32 v[44:45], v43
	v_cvt_f64_f32_e32 v[56:57], v39
	v_mul_f64 v[54:55], v[44:45], s[4:5]
	v_mul_f64 v[58:59], v[56:57], s[4:5]
	v_rndne_f64_e32 v[54:55], v[54:55]
	v_rndne_f64_e32 v[58:59], v[58:59]
	v_fma_f64 v[44:45], v[44:45], s[4:5], -v[54:55]
	v_fma_f64 v[56:57], v[56:57], s[4:5], -v[58:59]
	v_cvt_f32_f64_e32 v43, v[44:45]
	v_cvt_f32_f64_e32 v39, v[56:57]
	v_sin_f32_e32 v44, v43
	v_cos_f32_e32 v54, v43
	v_sin_f32_e32 v45, v39
	v_cos_f32_e32 v55, v39
	v_pk_mul_f32 v[56:57], v[44:45], v[20:21]
	v_pk_mul_f32 v[20:21], v[54:55], v[20:21]
	v_pk_fma_f32 v[56:57], v[54:55], v[22:23], v[56:57] neg_lo:[0,0,1] neg_hi:[0,0,1]
	v_pk_fma_f32 v[20:21], v[44:45], v[22:23], v[20:21]
	v_pk_mul_f32 v[22:23], v[14:15], v[16:17]
	v_pk_mul_f32 v[16:17], v[50:51], v[16:17]
	v_pk_fma_f32 v[22:23], v[50:51], v[36:37], v[22:23] neg_lo:[0,0,1] neg_hi:[0,0,1]
	v_pk_fma_f32 v[16:17], v[14:15], v[36:37], v[16:17]
	v_pk_mul_f32 v[14:15], v[44:45], v[12:13]
	v_pk_mul_f32 v[12:13], v[54:55], v[12:13]
	v_pk_fma_f32 v[14:15], v[54:55], v[18:19], v[14:15] neg_lo:[0,0,1] neg_hi:[0,0,1]
	v_pk_fma_f32 v[12:13], v[44:45], v[18:19], v[12:13]
	v_mov_b64_e32 v[18:19], v[14:15]
	v_mov_b64_e32 v[36:37], v[22:23]
	v_mov_b64_e32 v[22:23], v[56:57]
	v_mov_b64_e32 v[44:45], v[52:53]

; #define LAS __attribute__((address_space(3)))
; DI void moba_unit(const Params& P, int l, LAS char* lds, int b, int hd, int qb, int tid, int wave, int lane) {
;     ...
;     for (int n = 0; n < qb; ++n) {
;         float g = 0.f;
; #pragma unroll
;         for (int ks = 0; ks < 4; ++ks) { const f32x4 a = *(LAS const f32x4*)(kmL + n * 64 + 16 * ks + 8 * h), bq = *(LAS const f32x4*)(kmL + n * 64 + 16 * ks + 8 * h + 4);
;             g += (qv[ks][0] * a[0] + qv[ks][1] * a[1]) + (qv[ks][2] * a[2] + qv[ks][3] * a[3]) + (qv[ks][4] * bq[0] + qv[ks][5] * bq[1]) + (qv[ks][6] * bq[2] + qv[ks][7] * bq[3]); }
;         g += shx32(g, lane);
;         if (g > v0) { v2 = v1; i2 = i1; v1 = v0; i1 = i0; v0 = g; i0 = n; }
;         else if (g > v1) { v2 = v1; i2 = i1; v1 = g; i1 = n; }
;         else if (g > v2) { v2 = g; i2 = n; }
;     }
.LBB0_838:
	ds_read_b128 v[44:47], v33
	ds_read_b128 v[48:51], v33 offset:16
	s_waitcnt lgkmcnt(1)
	v_mov_b32_e32 v52, v45
	v_mov_b32_e32 v45, v47
	v_mov_b32_e32 v53, v46
	v_pk_mul_f32 v[44:45], v[44:45], v[0:1]
	s_waitcnt lgkmcnt(0)
	v_mov_b32_e32 v47, v48
	v_mov_b32_e32 v48, v51
	v_mov_b32_e32 v46, v50
	v_pk_fma_f32 v[44:45], v[52:53], v[2:3], v[44:45]
	v_pk_mul_f32 v[48:49], v[48:49], v[6:7]
	v_add_f32_e32 v43, v44, v45
	v_pk_fma_f32 v[48:49], v[46:47], v[4:5], v[48:49]
	ds_read_b128 v[44:47], v33 offset:64
	v_add_f32_e32 v43, v43, v49
	v_add_f32_e32 v43, v48, v43
	ds_read_b128 v[48:51], v33 offset:80
	v_add_f32_e32 v60, 0, v43
	s_waitcnt lgkmcnt(1)
	v_mov_b32_e32 v52, v45
	v_mov_b32_e32 v45, v47
	v_mov_b32_e32 v53, v46
	v_pk_mul_f32 v[44:45], v[44:45], v[8:9]
	s_waitcnt lgkmcnt(0)
	v_mov_b32_e32 v47, v48
	v_mov_b32_e32 v48, v51
	v_pk_fma_f32 v[44:45], v[52:53], v[10:11], v[44:45]
	v_mov_b32_e32 v46, v50
	v_pk_mul_f32 v[48:49], v[48:49], v[14:15]
	v_pk_add_f32 v[44:45], v[44:45], v[44:45] op_sel:[0,1] op_sel_hi:[1,0]
	v_pk_fma_f32 v[48:49], v[46:47], v[12:13], v[48:49]
	s_nop 0
	v_pk_add_f32 v[50:51], v[44:45], v[48:49] op_sel:[0,1] op_sel_hi:[1,0]
	ds_read_b128 v[44:47], v33 offset:192
	v_pk_add_f32 v[62:63], v[48:49], v[50:51]
	ds_read_b128 v[48:51], v33 offset:208
	ds_read_b128 v[52:55], v33 offset:128
	ds_read_b128 v[56:59], v33 offset:144
	s_waitcnt lgkmcnt(3)
	v_mul_f32_e32 v64, v47, v30
	v_mov_b32_e32 v47, v44
	s_waitcnt lgkmcnt(0)
	v_mov_b32_e32 v44, v57
	v_mul_f32_e32 v43, v46, v29
	v_mov_b32_e32 v46, v56
	v_pk_mul_f32 v[44:45], v[44:45], v[22:23]
	v_mul_f32_e32 v61, v50, v31
	v_pk_fma_f32 v[44:45], v[46:47], v[20:21], v[44:45]
	v_mul_f32_e32 v46, v53, v17
	v_mul_f32_e32 v50, v55, v19
	v_mul_f32_e32 v63, v51, v32
	v_pk_fma_f32 v[46:47], v[52:53], v[16:17], v[46:47] op_sel_hi:[1,1,0]
	v_pk_fma_f32 v[50:51], v[54:55], v[18:19], v[50:51] op_sel_hi:[1,1,0]
	v_mov_b32_e32 v47, v43
	v_mov_b32_e32 v51, v64
	v_pk_add_f32 v[46:47], v[46:47], v[50:51]
	s_nop 0
	v_pk_add_f32 v[44:45], v[44:45], v[46:47]
	v_mov_b32_e32 v47, v48
	v_mov_b32_e32 v48, v59
	v_mov_b32_e32 v46, v58
	v_pk_mul_f32 v[48:49], v[48:49], v[26:27]
	s_nop 0
	v_pk_fma_f32 v[46:47], v[46:47], v[24:25], v[48:49]
	s_nop 0
	v_pk_add_f32 v[44:45], v[44:45], v[46:47]
	v_pk_add_f32 v[46:47], v[60:61], v[62:63]
	s_nop 0
	v_pk_add_f32 v[44:45], v[46:47], v[44:45]
	s_nop 0
	v_add_f32_e32 v43, v44, v45
	v_mov_b32_e32 v44, v43
	v_mov_b32_e32 v45, v43
	s_nop 1
	v_permlane32_swap_b32_e32 v44, v45
	v_add_f32_e32 v44, v44, v45
	v_cmp_ngt_f32_e32 vcc, v44, v40
	v_mov_b32_e32 v43, s22
	v_mov_b32_e32 v45, v40
	s_and_saveexec_b64 s[0:1], vcc
	s_cbranch_execz .LBB0_844
	v_cmp_ngt_f32_e32 vcc, v44, v38
	v_mov_b32_e32 v46, s22
	s_and_saveexec_b64 s[34:35], vcc
	s_cbranch_execz .LBB0_843
	v_cmp_gt_f32_e32 vcc, v44, v42
	s_and_saveexec_b64 s[38:39], vcc
	v_mov_b32_e32 v41, s22
	v_mov_b32_e32 v42, v44
	s_or_b64 exec, exec, s[38:39]
	v_mov_b32_e32 v46, v39
	v_mov_b32_e32 v44, v38
	v_mov_b32_e32 v38, v42
	v_mov_b32_e32 v39, v41
